# attention layer prologue: lambda dot products via one load per lane + readlane fma chain (same order); cache_phase loads batched (fast path for the 256-WG grid)
# baseline (speedup 1.0000x reference)
.LBB0_321:
	s_load_dwordx2 s[4:5], s[60:61], 0xb0
	v_lshlrev_b32_e32 v0, 2, v221
	s_waitcnt lgkmcnt(0)
	global_load_dword v1, v0, s[4:5]
	global_load_dword v2, v0, s[4:5] offset:256
	global_load_dword v3, v0, s[4:5] offset:512
	global_load_dword v4, v0, s[4:5] offset:768
	s_waitcnt vmcnt(0)
	v_readlane_b32 s2, v1, 0
	v_readlane_b32 s3, v2, 0
	v_readlane_b32 s4, v3, 0
	v_readlane_b32 s5, v4, 0
	v_mov_b32_e32 v5, s3
	s_nop 0
	v_mov_b32_e32 v0, s5
	v_fma_f32 v154, s2, v5, v154
	v_fma_f32 v155, s4, v0, v155
	v_readlane_b32 s2, v1, 1
	v_readlane_b32 s3, v2, 1
	v_readlane_b32 s4, v3, 1
	v_readlane_b32 s5, v4, 1
	v_mov_b32_e32 v5, s3
	s_nop 0
	v_mov_b32_e32 v0, s5
	v_fma_f32 v154, s2, v5, v154
	v_fma_f32 v155, s4, v0, v155
	v_readlane_b32 s2, v1, 2
	v_readlane_b32 s3, v2, 2
	v_readlane_b32 s4, v3, 2
	v_readlane_b32 s5, v4, 2
	v_mov_b32_e32 v5, s3
	s_nop 0
	v_mov_b32_e32 v0, s5
	v_fma_f32 v154, s2, v5, v154
	v_fma_f32 v155, s4, v0, v155
	v_readlane_b32 s2, v1, 3
	v_readlane_b32 s3, v2, 3
	v_readlane_b32 s4, v3, 3
	v_readlane_b32 s5, v4, 3
	v_mov_b32_e32 v5, s3
	s_nop 0
	v_mov_b32_e32 v0, s5
	v_fma_f32 v154, s2, v5, v154
	v_fma_f32 v155, s4, v0, v155
	v_readlane_b32 s2, v1, 4
	v_readlane_b32 s3, v2, 4
	v_readlane_b32 s4, v3, 4
	v_readlane_b32 s5, v4, 4
	v_mov_b32_e32 v5, s3
	s_nop 0
	v_mov_b32_e32 v0, s5
	v_fma_f32 v154, s2, v5, v154
	v_fma_f32 v155, s4, v0, v155
	v_readlane_b32 s2, v1, 5
	v_readlane_b32 s3, v2, 5
	v_readlane_b32 s4, v3, 5
	v_readlane_b32 s5, v4, 5
	v_mov_b32_e32 v5, s3
	s_nop 0
	v_mov_b32_e32 v0, s5
	v_fma_f32 v154, s2, v5, v154
	v_fma_f32 v155, s4, v0, v155
	v_readlane_b32 s2, v1, 6
	v_readlane_b32 s3, v2, 6
	v_readlane_b32 s4, v3, 6
	v_readlane_b32 s5, v4, 6
	v_mov_b32_e32 v5, s3
	s_nop 0
	v_mov_b32_e32 v0, s5
	v_fma_f32 v154, s2, v5, v154
	v_fma_f32 v155, s4, v0, v155
	v_readlane_b32 s2, v1, 7
	v_readlane_b32 s3, v2, 7
	v_readlane_b32 s4, v3, 7
	v_readlane_b32 s5, v4, 7
	v_mov_b32_e32 v5, s3
	s_nop 0
	v_mov_b32_e32 v0, s5
	v_fma_f32 v154, s2, v5, v154
	v_fma_f32 v155, s4, v0, v155
	v_readlane_b32 s2, v1, 8
	v_readlane_b32 s3, v2, 8
	v_readlane_b32 s4, v3, 8
	v_readlane_b32 s5, v4, 8
	v_mov_b32_e32 v5, s3
	s_nop 0
	v_mov_b32_e32 v0, s5
	v_fma_f32 v154, s2, v5, v154
	v_fma_f32 v155, s4, v0, v155
	v_readlane_b32 s2, v1, 9
	v_readlane_b32 s3, v2, 9
	v_readlane_b32 s4, v3, 9
	v_readlane_b32 s5, v4, 9
	v_mov_b32_e32 v5, s3
	s_nop 0
	v_mov_b32_e32 v0, s5
	v_fma_f32 v154, s2, v5, v154
	v_fma_f32 v155, s4, v0, v155
	v_readlane_b32 s2, v1, 10
	v_readlane_b32 s3, v2, 10
	v_readlane_b32 s4, v3, 10
	v_readlane_b32 s5, v4, 10
	v_mov_b32_e32 v5, s3
	s_nop 0
	v_mov_b32_e32 v0, s5
	v_fma_f32 v154, s2, v5, v154
	v_fma_f32 v155, s4, v0, v155
	v_readlane_b32 s2, v1, 11
	v_readlane_b32 s3, v2, 11
	v_readlane_b32 s4, v3, 11
	v_readlane_b32 s5, v4, 11
	v_mov_b32_e32 v5, s3
	s_nop 0
	v_mov_b32_e32 v0, s5
	v_fma_f32 v154, s2, v5, v154
	v_fma_f32 v155, s4, v0, v155
	v_readlane_b32 s2, v1, 12
	v_readlane_b32 s3, v2, 12
	v_readlane_b32 s4, v3, 12
	v_readlane_b32 s5, v4, 12
	v_mov_b32_e32 v5, s3
	s_nop 0
	v_mov_b32_e32 v0, s5
	v_fma_f32 v154, s2, v5, v154
	v_fma_f32 v155, s4, v0, v155
	v_readlane_b32 s2, v1, 13
	v_readlane_b32 s3, v2, 13
	v_readlane_b32 s4, v3, 13
	v_readlane_b32 s5, v4, 13
	v_mov_b32_e32 v5, s3
	s_nop 0
	v_mov_b32_e32 v0, s5
	v_fma_f32 v154, s2, v5, v154
	v_fma_f32 v155, s4, v0, v155
	v_readlane_b32 s2, v1, 14
	v_readlane_b32 s3, v2, 14
	v_readlane_b32 s4, v3, 14
	v_readlane_b32 s5, v4, 14
	v_mov_b32_e32 v5, s3
	s_nop 0
	v_mov_b32_e32 v0, s5
	v_fma_f32 v154, s2, v5, v154
	v_fma_f32 v155, s4, v0, v155
	v_readlane_b32 s2, v1, 15
	v_readlane_b32 s3, v2, 15
	v_readlane_b32 s4, v3, 15
	v_readlane_b32 s5, v4, 15
	v_mov_b32_e32 v5, s3
	s_nop 0
	v_mov_b32_e32 v0, s5
	v_fma_f32 v154, s2, v5, v154
	v_fma_f32 v155, s4, v0, v155
	v_readlane_b32 s2, v1, 16
	v_readlane_b32 s3, v2, 16
	v_readlane_b32 s4, v3, 16
	v_readlane_b32 s5, v4, 16
	v_mov_b32_e32 v5, s3
	s_nop 0
	v_mov_b32_e32 v0, s5
	v_fma_f32 v154, s2, v5, v154
	v_fma_f32 v155, s4, v0, v155
	v_readlane_b32 s2, v1, 17
	v_readlane_b32 s3, v2, 17
	v_readlane_b32 s4, v3, 17
	v_readlane_b32 s5, v4, 17
	v_mov_b32_e32 v5, s3
	s_nop 0
	v_mov_b32_e32 v0, s5
	v_fma_f32 v154, s2, v5, v154
	v_fma_f32 v155, s4, v0, v155
	v_readlane_b32 s2, v1, 18
	v_readlane_b32 s3, v2, 18
	v_readlane_b32 s4, v3, 18
	v_readlane_b32 s5, v4, 18
	v_mov_b32_e32 v5, s3
	s_nop 0
	v_mov_b32_e32 v0, s5
	v_fma_f32 v154, s2, v5, v154
	v_fma_f32 v155, s4, v0, v155
	v_readlane_b32 s2, v1, 19
	v_readlane_b32 s3, v2, 19
	v_readlane_b32 s4, v3, 19
	v_readlane_b32 s5, v4, 19
	v_mov_b32_e32 v5, s3
	s_nop 0
	v_mov_b32_e32 v0, s5
	v_fma_f32 v154, s2, v5, v154
	v_fma_f32 v155, s4, v0, v155
	v_readlane_b32 s2, v1, 20
	v_readlane_b32 s3, v2, 20
	v_readlane_b32 s4, v3, 20
	v_readlane_b32 s5, v4, 20
	v_mov_b32_e32 v5, s3
	s_nop 0
	v_mov_b32_e32 v0, s5
	v_fma_f32 v154, s2, v5, v154
	v_fma_f32 v155, s4, v0, v155
	v_readlane_b32 s2, v1, 21
	v_readlane_b32 s3, v2, 21
	v_readlane_b32 s4, v3, 21
	v_readlane_b32 s5, v4, 21
	v_mov_b32_e32 v5, s3
	s_nop 0
	v_mov_b32_e32 v0, s5
	v_fma_f32 v154, s2, v5, v154
	v_fma_f32 v155, s4, v0, v155
	v_readlane_b32 s2, v1, 22
	v_readlane_b32 s3, v2, 22
	v_readlane_b32 s4, v3, 22
	v_readlane_b32 s5, v4, 22
	v_mov_b32_e32 v5, s3
	s_nop 0
	v_mov_b32_e32 v0, s5
	v_fma_f32 v154, s2, v5, v154
	v_fma_f32 v155, s4, v0, v155
	v_readlane_b32 s2, v1, 23
	v_readlane_b32 s3, v2, 23
	v_readlane_b32 s4, v3, 23
	v_readlane_b32 s5, v4, 23
	v_mov_b32_e32 v5, s3
	s_nop 0
	v_mov_b32_e32 v0, s5
	v_fma_f32 v154, s2, v5, v154
	v_fma_f32 v155, s4, v0, v155
	v_readlane_b32 s2, v1, 24
	v_readlane_b32 s3, v2, 24
	v_readlane_b32 s4, v3, 24
	v_readlane_b32 s5, v4, 24
	v_mov_b32_e32 v5, s3
	s_nop 0
	v_mov_b32_e32 v0, s5
	v_fma_f32 v154, s2, v5, v154
	v_fma_f32 v155, s4, v0, v155
	v_readlane_b32 s2, v1, 25
	v_readlane_b32 s3, v2, 25
	v_readlane_b32 s4, v3, 25
	v_readlane_b32 s5, v4, 25
	v_mov_b32_e32 v5, s3
	s_nop 0
	v_mov_b32_e32 v0, s5
	v_fma_f32 v154, s2, v5, v154
	v_fma_f32 v155, s4, v0, v155
	v_readlane_b32 s2, v1, 26
	v_readlane_b32 s3, v2, 26
	v_readlane_b32 s4, v3, 26
	v_readlane_b32 s5, v4, 26
	v_mov_b32_e32 v5, s3
	s_nop 0
	v_mov_b32_e32 v0, s5
	v_fma_f32 v154, s2, v5, v154
	v_fma_f32 v155, s4, v0, v155
	v_readlane_b32 s2, v1, 27
	v_readlane_b32 s3, v2, 27
	v_readlane_b32 s4, v3, 27
	v_readlane_b32 s5, v4, 27
	v_mov_b32_e32 v5, s3
	s_nop 0
	v_mov_b32_e32 v0, s5
	v_fma_f32 v154, s2, v5, v154
	v_fma_f32 v155, s4, v0, v155
	v_readlane_b32 s2, v1, 28
	v_readlane_b32 s3, v2, 28
	v_readlane_b32 s4, v3, 28
	v_readlane_b32 s5, v4, 28
	v_mov_b32_e32 v5, s3
	s_nop 0
	v_mov_b32_e32 v0, s5
	v_fma_f32 v154, s2, v5, v154
	v_fma_f32 v155, s4, v0, v155
	v_readlane_b32 s2, v1, 29
	v_readlane_b32 s3, v2, 29
	v_readlane_b32 s4, v3, 29
	v_readlane_b32 s5, v4, 29
	v_mov_b32_e32 v5, s3
	s_nop 0
	v_mov_b32_e32 v0, s5
	v_fma_f32 v154, s2, v5, v154
	v_fma_f32 v155, s4, v0, v155
	v_readlane_b32 s2, v1, 30
	v_readlane_b32 s3, v2, 30
	v_readlane_b32 s4, v3, 30
	v_readlane_b32 s5, v4, 30
	v_mov_b32_e32 v5, s3
	s_nop 0
	v_mov_b32_e32 v0, s5
	v_fma_f32 v154, s2, v5, v154
	v_fma_f32 v155, s4, v0, v155
	v_readlane_b32 s2, v1, 31
	v_readlane_b32 s3, v2, 31
	v_readlane_b32 s4, v3, 31
	v_readlane_b32 s5, v4, 31
	v_mov_b32_e32 v5, s3
	s_nop 0
	v_mov_b32_e32 v0, s5
	v_fma_f32 v154, s2, v5, v154
	v_fma_f32 v155, s4, v0, v155
	v_readlane_b32 s2, v1, 32
	v_readlane_b32 s3, v2, 32
	v_readlane_b32 s4, v3, 32
	v_readlane_b32 s5, v4, 32
	v_mov_b32_e32 v5, s3
	s_nop 0
	v_mov_b32_e32 v0, s5
	v_fma_f32 v154, s2, v5, v154
	v_fma_f32 v155, s4, v0, v155
	v_readlane_b32 s2, v1, 33
	v_readlane_b32 s3, v2, 33
	v_readlane_b32 s4, v3, 33
	v_readlane_b32 s5, v4, 33
	v_mov_b32_e32 v5, s3
	s_nop 0
	v_mov_b32_e32 v0, s5
	v_fma_f32 v154, s2, v5, v154
	v_fma_f32 v155, s4, v0, v155
	v_readlane_b32 s2, v1, 34
	v_readlane_b32 s3, v2, 34
	v_readlane_b32 s4, v3, 34
	v_readlane_b32 s5, v4, 34
	v_mov_b32_e32 v5, s3
	s_nop 0
	v_mov_b32_e32 v0, s5
	v_fma_f32 v154, s2, v5, v154
	v_fma_f32 v155, s4, v0, v155
	v_readlane_b32 s2, v1, 35
	v_readlane_b32 s3, v2, 35
	v_readlane_b32 s4, v3, 35
	v_readlane_b32 s5, v4, 35
	v_mov_b32_e32 v5, s3
	s_nop 0
	v_mov_b32_e32 v0, s5
	v_fma_f32 v154, s2, v5, v154
	v_fma_f32 v155, s4, v0, v155
	v_readlane_b32 s2, v1, 36
	v_readlane_b32 s3, v2, 36
	v_readlane_b32 s4, v3, 36
	v_readlane_b32 s5, v4, 36
	v_mov_b32_e32 v5, s3
	s_nop 0
	v_mov_b32_e32 v0, s5
	v_fma_f32 v154, s2, v5, v154
	v_fma_f32 v155, s4, v0, v155
	v_readlane_b32 s2, v1, 37
	v_readlane_b32 s3, v2, 37
	v_readlane_b32 s4, v3, 37
	v_readlane_b32 s5, v4, 37
	v_mov_b32_e32 v5, s3
	s_nop 0
	v_mov_b32_e32 v0, s5
	v_fma_f32 v154, s2, v5, v154
	v_fma_f32 v155, s4, v0, v155
	v_readlane_b32 s2, v1, 38
	v_readlane_b32 s3, v2, 38
	v_readlane_b32 s4, v3, 38
	v_readlane_b32 s5, v4, 38
	v_mov_b32_e32 v5, s3
	s_nop 0
	v_mov_b32_e32 v0, s5
	v_fma_f32 v154, s2, v5, v154
	v_fma_f32 v155, s4, v0, v155
	v_readlane_b32 s2, v1, 39
	v_readlane_b32 s3, v2, 39
	v_readlane_b32 s4, v3, 39
	v_readlane_b32 s5, v4, 39
	v_mov_b32_e32 v5, s3
	s_nop 0
	v_mov_b32_e32 v0, s5
	v_fma_f32 v154, s2, v5, v154
	v_fma_f32 v155, s4, v0, v155
	v_readlane_b32 s2, v1, 40
	v_readlane_b32 s3, v2, 40
	v_readlane_b32 s4, v3, 40
	v_readlane_b32 s5, v4, 40
	v_mov_b32_e32 v5, s3
	s_nop 0
	v_mov_b32_e32 v0, s5
	v_fma_f32 v154, s2, v5, v154
	v_fma_f32 v155, s4, v0, v155
	v_readlane_b32 s2, v1, 41
	v_readlane_b32 s3, v2, 41
	v_readlane_b32 s4, v3, 41
	v_readlane_b32 s5, v4, 41
	v_mov_b32_e32 v5, s3
	s_nop 0
	v_mov_b32_e32 v0, s5
	v_fma_f32 v154, s2, v5, v154
	v_fma_f32 v155, s4, v0, v155
	v_readlane_b32 s2, v1, 42
	v_readlane_b32 s3, v2, 42
	v_readlane_b32 s4, v3, 42
	v_readlane_b32 s5, v4, 42
	v_mov_b32_e32 v5, s3
	s_nop 0
	v_mov_b32_e32 v0, s5
	v_fma_f32 v154, s2, v5, v154
	v_fma_f32 v155, s4, v0, v155
	v_readlane_b32 s2, v1, 43
	v_readlane_b32 s3, v2, 43
	v_readlane_b32 s4, v3, 43
	v_readlane_b32 s5, v4, 43
	v_mov_b32_e32 v5, s3
	s_nop 0
	v_mov_b32_e32 v0, s5
	v_fma_f32 v154, s2, v5, v154
	v_fma_f32 v155, s4, v0, v155
	v_readlane_b32 s2, v1, 44
	v_readlane_b32 s3, v2, 44
	v_readlane_b32 s4, v3, 44
	v_readlane_b32 s5, v4, 44
	v_mov_b32_e32 v5, s3
	s_nop 0
	v_mov_b32_e32 v0, s5
	v_fma_f32 v154, s2, v5, v154
	v_fma_f32 v155, s4, v0, v155
	v_readlane_b32 s2, v1, 45
	v_readlane_b32 s3, v2, 45
	v_readlane_b32 s4, v3, 45
	v_readlane_b32 s5, v4, 45
	v_mov_b32_e32 v5, s3
	s_nop 0
	v_mov_b32_e32 v0, s5
	v_fma_f32 v154, s2, v5, v154
	v_fma_f32 v155, s4, v0, v155
	v_readlane_b32 s2, v1, 46
	v_readlane_b32 s3, v2, 46
	v_readlane_b32 s4, v3, 46
	v_readlane_b32 s5, v4, 46
	v_mov_b32_e32 v5, s3
	s_nop 0
	v_mov_b32_e32 v0, s5
	v_fma_f32 v154, s2, v5, v154
	v_fma_f32 v155, s4, v0, v155
	v_readlane_b32 s2, v1, 47
	v_readlane_b32 s3, v2, 47
	v_readlane_b32 s4, v3, 47
	v_readlane_b32 s5, v4, 47
	v_mov_b32_e32 v5, s3
	s_nop 0
	v_mov_b32_e32 v0, s5
	v_fma_f32 v154, s2, v5, v154
	v_fma_f32 v155, s4, v0, v155
	v_readlane_b32 s2, v1, 48
	v_readlane_b32 s3, v2, 48
	v_readlane_b32 s4, v3, 48
	v_readlane_b32 s5, v4, 48
	v_mov_b32_e32 v5, s3
	s_nop 0
	v_mov_b32_e32 v0, s5
	v_fma_f32 v154, s2, v5, v154
	v_fma_f32 v155, s4, v0, v155
	v_readlane_b32 s2, v1, 49
	v_readlane_b32 s3, v2, 49
	v_readlane_b32 s4, v3, 49
	v_readlane_b32 s5, v4, 49
	v_mov_b32_e32 v5, s3
	s_nop 0
	v_mov_b32_e32 v0, s5
	v_fma_f32 v154, s2, v5, v154
	v_fma_f32 v155, s4, v0, v155
	v_readlane_b32 s2, v1, 50
	v_readlane_b32 s3, v2, 50
	v_readlane_b32 s4, v3, 50
	v_readlane_b32 s5, v4, 50
	v_mov_b32_e32 v5, s3
	s_nop 0
	v_mov_b32_e32 v0, s5
	v_fma_f32 v154, s2, v5, v154
	v_fma_f32 v155, s4, v0, v155
	v_readlane_b32 s2, v1, 51
	v_readlane_b32 s3, v2, 51
	v_readlane_b32 s4, v3, 51
	v_readlane_b32 s5, v4, 51
	v_mov_b32_e32 v5, s3
	s_nop 0
	v_mov_b32_e32 v0, s5
	v_fma_f32 v154, s2, v5, v154
	v_fma_f32 v155, s4, v0, v155
	v_readlane_b32 s2, v1, 52
	v_readlane_b32 s3, v2, 52
	v_readlane_b32 s4, v3, 52
	v_readlane_b32 s5, v4, 52
	v_mov_b32_e32 v5, s3
	s_nop 0
	v_mov_b32_e32 v0, s5
	v_fma_f32 v154, s2, v5, v154
	v_fma_f32 v155, s4, v0, v155
	v_readlane_b32 s2, v1, 53
	v_readlane_b32 s3, v2, 53
	v_readlane_b32 s4, v3, 53
	v_readlane_b32 s5, v4, 53
	v_mov_b32_e32 v5, s3
	s_nop 0
	v_mov_b32_e32 v0, s5
	v_fma_f32 v154, s2, v5, v154
	v_fma_f32 v155, s4, v0, v155
	v_readlane_b32 s2, v1, 54
	v_readlane_b32 s3, v2, 54
	v_readlane_b32 s4, v3, 54
	v_readlane_b32 s5, v4, 54
	v_mov_b32_e32 v5, s3
	s_nop 0
	v_mov_b32_e32 v0, s5
	v_fma_f32 v154, s2, v5, v154
	v_fma_f32 v155, s4, v0, v155
	v_readlane_b32 s2, v1, 55
	v_readlane_b32 s3, v2, 55
	v_readlane_b32 s4, v3, 55
	v_readlane_b32 s5, v4, 55
	v_mov_b32_e32 v5, s3
	s_nop 0
	v_mov_b32_e32 v0, s5
	v_fma_f32 v154, s2, v5, v154
	v_fma_f32 v155, s4, v0, v155
	v_readlane_b32 s2, v1, 56
	v_readlane_b32 s3, v2, 56
	v_readlane_b32 s4, v3, 56
	v_readlane_b32 s5, v4, 56
	v_mov_b32_e32 v5, s3
	s_nop 0
	v_mov_b32_e32 v0, s5
	v_fma_f32 v154, s2, v5, v154
	v_fma_f32 v155, s4, v0, v155
	v_readlane_b32 s2, v1, 57
	v_readlane_b32 s3, v2, 57
	v_readlane_b32 s4, v3, 57
	v_readlane_b32 s5, v4, 57
	v_mov_b32_e32 v5, s3
	s_nop 0
	v_mov_b32_e32 v0, s5
	v_fma_f32 v154, s2, v5, v154
	v_fma_f32 v155, s4, v0, v155
	v_readlane_b32 s2, v1, 58
	v_readlane_b32 s3, v2, 58
	v_readlane_b32 s4, v3, 58
	v_readlane_b32 s5, v4, 58
	v_mov_b32_e32 v5, s3
	s_nop 0
	v_mov_b32_e32 v0, s5
	v_fma_f32 v154, s2, v5, v154
	v_fma_f32 v155, s4, v0, v155
	v_readlane_b32 s2, v1, 59
	v_readlane_b32 s3, v2, 59
	v_readlane_b32 s4, v3, 59
	v_readlane_b32 s5, v4, 59
	v_mov_b32_e32 v5, s3
	s_nop 0
	v_mov_b32_e32 v0, s5
	v_fma_f32 v154, s2, v5, v154
	v_fma_f32 v155, s4, v0, v155
	v_readlane_b32 s2, v1, 60
	v_readlane_b32 s3, v2, 60
	v_readlane_b32 s4, v3, 60
	v_readlane_b32 s5, v4, 60
	v_mov_b32_e32 v5, s3
	s_nop 0
	v_mov_b32_e32 v0, s5
	v_fma_f32 v154, s2, v5, v154
	v_fma_f32 v155, s4, v0, v155
	v_readlane_b32 s2, v1, 61
	v_readlane_b32 s3, v2, 61
	v_readlane_b32 s4, v3, 61
	v_readlane_b32 s5, v4, 61
	v_mov_b32_e32 v5, s3
	s_nop 0
	v_mov_b32_e32 v0, s5
	v_fma_f32 v154, s2, v5, v154
	v_fma_f32 v155, s4, v0, v155
	v_readlane_b32 s2, v1, 62
	v_readlane_b32 s3, v2, 62
	v_readlane_b32 s4, v3, 62
	v_readlane_b32 s5, v4, 62
	v_mov_b32_e32 v5, s3
	s_nop 0
	v_mov_b32_e32 v0, s5
	v_fma_f32 v154, s2, v5, v154
	v_fma_f32 v155, s4, v0, v155
	v_readlane_b32 s2, v1, 63
	v_readlane_b32 s3, v2, 63
	v_readlane_b32 s4, v3, 63
	v_readlane_b32 s5, v4, 63
	v_mov_b32_e32 v5, s3
	s_nop 0
	v_mov_b32_e32 v0, s5
	v_fma_f32 v154, s2, v5, v154
	v_fma_f32 v155, s4, v0, v155
	s_mov_b64 s[10:11], s[60:61]
	s_mov_b64 s[16:17], s[60:61]
	v_mov_b32_e32 v0, v219
	s_add_u32 s4, s14, 0x7210000
	v_readfirstlane_b32 s2, v0
	v_mov_b32_e32 v0, v218
	s_addc_u32 s5, s15, 0
	s_add_u32 s6, s12, 0x9410000
	v_lshl_add_u32 v0, s2, 8, v0
	s_mov_b32 s2, 0x100000
	s_addc_u32 s7, s13, 0
	v_cmp_gt_i32_e32 vcc, s2, v0
	s_and_saveexec_b64 s[2:3], vcc
	v_readlane_b32 s22, v252, 4
	s_cbranch_execz .LBB0_325
	s_load_dwordx2 s[10:11], s[10:11], 0x18
	s_nop 0
	s_load_dwordx2 s[16:17], s[16:17], 0x20
	s_mov_b64 s[18:19], 0
	s_cmp_eq_u32 s22, 0x20000
	s_cbranch_scc0 .LBB0_324
	v_and_b32_e32 v6, 0x3ff, v0
	v_lshrrev_b32_e32 v7, 10, v0
	v_lshlrev_b32_e32 v1, 2, v0
	v_add_u32_e32 v2, 0x2000, v7
	v_lshlrev_b32_e32 v2, 11, v2
	v_lshl_add_u32 v2, v6, 1, v2
	v_mul_u32_u24_e32 v3, 0x1200, v6
	v_lshl_add_u32 v3, v7, 1, v3
	v_add_u32_e32 v3, 0x1000000, v3
	s_waitcnt lgkmcnt(0)
	global_load_dword v8, v1, s[10:11]
	global_load_dword v16, v1, s[16:17]
	s_add_u32 s10, s10, 0x80000
	s_addc_u32 s11, s11, 0
	s_add_u32 s16, s16, 0x80000
	s_addc_u32 s17, s17, 0
	global_load_dword v9, v1, s[10:11]
	global_load_dword v17, v1, s[16:17]
	s_add_u32 s10, s10, 0x80000
	s_addc_u32 s11, s11, 0
	s_add_u32 s16, s16, 0x80000
	s_addc_u32 s17, s17, 0
	global_load_dword v10, v1, s[10:11]
	global_load_dword v18, v1, s[16:17]
	s_add_u32 s10, s10, 0x80000
	s_addc_u32 s11, s11, 0
	s_add_u32 s16, s16, 0x80000
	s_addc_u32 s17, s17, 0
	global_load_dword v11, v1, s[10:11]
	global_load_dword v19, v1, s[16:17]
	s_add_u32 s10, s10, 0x80000
	s_addc_u32 s11, s11, 0
	s_add_u32 s16, s16, 0x80000
	s_addc_u32 s17, s17, 0
	global_load_dword v12, v1, s[10:11]
	global_load_dword v20, v1, s[16:17]
	s_add_u32 s10, s10, 0x80000
	s_addc_u32 s11, s11, 0
	s_add_u32 s16, s16, 0x80000
	s_addc_u32 s17, s17, 0
	global_load_dword v13, v1, s[10:11]
	global_load_dword v21, v1, s[16:17]
	s_add_u32 s10, s10, 0x80000
	s_addc_u32 s11, s11, 0
	s_add_u32 s16, s16, 0x80000
	s_addc_u32 s17, s17, 0
	global_load_dword v14, v1, s[10:11]
	global_load_dword v22, v1, s[16:17]
	s_add_u32 s10, s10, 0x80000
	s_addc_u32 s11, s11, 0
	s_add_u32 s16, s16, 0x80000
	s_addc_u32 s17, s17, 0
	global_load_dword v15, v1, s[10:11]
	global_load_dword v23, v1, s[16:17]
	s_add_u32 s18, s4, 0x0
	s_addc_u32 s19, s5, 0
	s_add_u32 s20, s6, 0x0
	s_addc_u32 s21, s7, 0
	s_waitcnt vmcnt(14)
	v_cvt_pk_bf16_f32 v8, v8, v8
	v_cvt_pk_bf16_f32 v16, v16, v16
	global_store_short v2, v8, s[18:19]
	global_store_short v3, v16, s[20:21]
	s_add_u32 s18, s4, 0x40000
	s_addc_u32 s19, s5, 0
	s_add_u32 s20, s6, 0x100
	s_addc_u32 s21, s7, 0
	s_waitcnt vmcnt(14)
	v_cvt_pk_bf16_f32 v9, v9, v9
	v_cvt_pk_bf16_f32 v17, v17, v17
	global_store_short v2, v9, s[18:19]
	global_store_short v3, v17, s[20:21]
	s_add_u32 s18, s4, 0x480000
	s_addc_u32 s19, s5, 0
	s_add_u32 s20, s6, 0x480000
	s_addc_u32 s21, s7, 0
	s_waitcnt vmcnt(14)
	v_cvt_pk_bf16_f32 v10, v10, v10
	v_cvt_pk_bf16_f32 v18, v18, v18
	global_store_short v2, v10, s[18:19]
	global_store_short v3, v18, s[20:21]
	s_add_u32 s18, s4, 0x4c0000
	s_addc_u32 s19, s5, 0
	s_add_u32 s20, s6, 0x480100
	s_addc_u32 s21, s7, 0
	s_waitcnt vmcnt(14)
	v_cvt_pk_bf16_f32 v11, v11, v11
	v_cvt_pk_bf16_f32 v19, v19, v19
	global_store_short v2, v11, s[18:19]
	global_store_short v3, v19, s[20:21]
	s_add_u32 s18, s4, 0x900000
	s_addc_u32 s19, s5, 0
	s_add_u32 s20, s6, 0x900000
	s_addc_u32 s21, s7, 0
	s_waitcnt vmcnt(14)
	v_cvt_pk_bf16_f32 v12, v12, v12
	v_cvt_pk_bf16_f32 v20, v20, v20
	global_store_short v2, v12, s[18:19]
	global_store_short v3, v20, s[20:21]
	s_add_u32 s18, s4, 0x940000
	s_addc_u32 s19, s5, 0
	s_add_u32 s20, s6, 0x900100
	s_addc_u32 s21, s7, 0
	s_waitcnt vmcnt(14)
	v_cvt_pk_bf16_f32 v13, v13, v13
	v_cvt_pk_bf16_f32 v21, v21, v21
	global_store_short v2, v13, s[18:19]
	global_store_short v3, v21, s[20:21]
	s_add_u32 s18, s4, 0xd80000
	s_addc_u32 s19, s5, 0
	s_add_u32 s20, s6, 0xd80000
	s_addc_u32 s21, s7, 0
	s_waitcnt vmcnt(14)
	v_cvt_pk_bf16_f32 v14, v14, v14
	v_cvt_pk_bf16_f32 v22, v22, v22
	global_store_short v2, v14, s[18:19]
	global_store_short v3, v22, s[20:21]
	s_add_u32 s18, s4, 0xdc0000
	s_addc_u32 s19, s5, 0
	s_add_u32 s20, s6, 0xd80100
	s_addc_u32 s21, s7, 0
	s_waitcnt vmcnt(14)
	v_cvt_pk_bf16_f32 v15, v15, v15
	v_cvt_pk_bf16_f32 v23, v23, v23
	global_store_short v2, v15, s[18:19]
	global_store_short v3, v23, s[20:21]
	s_branch .LBB0_325
